# mixer item loops: per-item LDS parameter reads issued together with one wait; in-proj and FFN-up next-unit index: exact multiply-shift instead of the reciprocal division sequence
# speedup vs baseline: 1.0054x; 1.0054x over previous
;     __device__ bool next(int i, Unit& u) const {
;         const long L = (long)i * G + c; if (L >= nwg) return false;
;         int wgid = (int)L; { const int q = nwg / NXCD, r = nwg % NXCD, xcd = wgid % NXCD, off = wgid / NXCD; wgid = (xcd < r ? xcd * (q + 1) : r * (q + 1) + (xcd - r) * q) + off; }
;         const int nig = WGM * nN, gid = wgid / nig, fm = gid * WGM, gsz = (nM - fm) < WGM ? (nM - fm) : WGM;
;         u.pm = fm + ((wgid % nig) % gsz); u.pn = (wgid % nig) / gsz; return true;
.LBB0_79:
	s_add_i32 s73, s73, 1
	s_mul_i32 s4, s73, s35
	s_mul_hi_u32 s5, s73, s3
	s_add_i32 s5, s5, s4
	s_mul_i32 s4, s73, s3
	s_add_u32 s14, s4, s1
	s_addc_u32 s15, s5, s37
	v_cmp_gt_i64_e64 s[4:5], s[14:15], v[238:239]
	s_and_b64 vcc, exec, s[4:5]
	s_cbranch_vccnz .LBB0_81
	s_ashr_i32 s8, s14, 31
	s_lshr_b32 s8, s8, 29
	s_add_i32 s8, s14, s8
	s_ashr_i32 s9, s8, 3
	s_and_b32 s8, s8, -8
	s_sub_i32 s8, s14, s8
	s_cmp_lt_i32 s8, 0
	s_movk_i32 s12, 0xb1
	s_cselect_b32 s12, s12, 0xb0
	s_mul_i32 s8, s12, s8
	s_add_i32 s8, s8, s9
	s_mul_hi_i32 s9, s8, 0x3e0f83e1
	s_lshr_b32 s12, s9, 31
	s_ashr_i32 s9, s9, 5
	s_add_i32 s9, s9, s12
	s_mul_i32 s12, s9, 6
	s_sub_i32 s13, 64, s12
	s_min_i32 s13, s13, 6
	s_mulk_i32 s9, 0x84
	s_sub_i32 s9, s8, s9
	s_movk_i32 s22, 0x2aab
	s_cmp_eq_u32 s13, 6
	s_cselect_b32 s22, s22, 0x4000
	s_mul_i32 s8, s9, s22
	s_lshr_b32 s8, s8, 16
	s_mul_i32 s13, s8, s13
	s_sub_i32 s9, s9, s13
	s_add_i32 s12, s9, s12

; __device__ __forceinline__ int opaque_bid() { int t = blockIdx.x; asm volatile("" : "+s"(t)); return t; }
; __device__ __forceinline__ int opaque_gd() { int t = gridDim.x; asm volatile("" : "+s"(t)); return t; }
; __device__ __forceinline__ int opaque_tid() { int t = threadIdx.x; asm volatile("" : "+v"(t)); return t; }
; __device__ __forceinline__ Params fetchP(const LAS Params* lp0) { unsigned la = (unsigned)(unsigned long long)lp0; asm volatile("" : "+v"(la)); const LAS Params* lp = (const LAS Params*)la; Params q; PFIELDS(PFETCH) q.ph_lo = 0; q.ph_hi = 0; return q; }
; __device__ __forceinline__ void lru_fix_item(const Params& p, int l, int item) {
;     const int tid = opaque_tid(), wid = tid >> 6, lane = tid & 63;
;     const int b = item >> 6, h = (item >> 4) & 3, seg = item & 15;
;     const int t0 = seg * 128 + wid * 16; const size_t Tb = (size_t)b * SEQ;
;     const int ch = h * 64 + lane;
;     const float* sc = (const float*)p.hbuf + ((((size_t)b * 4 + h) * 16 + seg) * 8 + wid) * 2048 + lane * 16;
;     f32x4 hv[4], av[4]; unsigned gr[16];
; #pragma unroll
;     for (int q = 0; q < 4; ++q) { hv[q] = *(const f32x4*)(sc + q * 4); av[q] = *(const f32x4*)(sc + 1024 + q * 4); }
; #pragma unroll
;     for (int i = 0; i < 16; ++i) gr[i] = p.z[(Tb + t0 + i) * ZLD + 2560 + ch];
; __device__ __forceinline__ void run_phase(const LAS Params* lp, int ph, LAS unsigned char* lds) {
;     ...
;     case 2: for (int it = opaque_bid(); it < 1280; it += opaque_gd()) { const Params p = fetchP(lp); const int jx = (it & ~255) + (it & 7) * 32 + ((it & 255) >> 3);
;             if (it < 256) hgrn_item(p, l, jx, 1, lds); else if (it < 768) gmlp_item(p, l, jx - 256, lds); else lru_fix_item(p, l, jx - 768); } break;
.LBB0_307:
	v_mov_b32_e32 v0, s84
	ds_read2_b64 v[12:15], v0 offset0:8 offset1:9
	ds_read2_b64 v[8:11], v0 offset0:29 offset1:30
	ds_read2_b64 v[16:19], v0 offset0:11 offset1:31
	ds_read2_b64 v[20:23], v0 offset0:33 offset1:37
	ds_read2_b64 v[4:7], v0 offset0:39 offset1:40
	ds_read_b64 v[0:1], v0 offset:328
	s_lshl_b32 s7, s72, 5
	s_and_b32 s6, s72, 0xffffff00
	s_and_b32 s7, s7, 0xe0
	s_or_b32 s21, s7, s6
	s_mov_b64 s[6:7], -1
	s_cmpk_gt_i32 s72, 0xff
	s_waitcnt lgkmcnt(0)
	v_readfirstlane_b32 s2, v12
	v_readfirstlane_b32 s20, v13
	v_readfirstlane_b32 s23, v14
	v_readfirstlane_b32 s36, v15
	v_readfirstlane_b32 s34, v8
	v_readfirstlane_b32 s35, v9
	v_readfirstlane_b32 s9, v10
	v_readfirstlane_b32 s0, v16
	v_readfirstlane_b32 s14, v17
	v_readfirstlane_b32 s30, v18
	v_readfirstlane_b32 s31, v19
	v_readfirstlane_b32 s33, v11
	v_readfirstlane_b32 s4, v20
	v_readfirstlane_b32 s5, v21
	v_readfirstlane_b32 s18, v22
	v_readfirstlane_b32 s19, v23
	v_readfirstlane_b32 s15, v4
	v_readfirstlane_b32 s17, v5
	v_readfirstlane_b32 s10, v6
	v_readfirstlane_b32 s11, v7
	v_readfirstlane_b32 s12, v0
	v_readfirstlane_b32 s13, v1
	s_cbranch_scc0 .LBB0_326
	s_bfe_u32 s6, s72, 0x50003
	s_or_b32 s16, s21, s6
	s_cmpk_gt_u32 s72, 0x2ff
	s_mov_b64 s[6:7], -1
	s_cbranch_scc0 .LBB0_319
	s_add_i32 s6, s21, 0xfffffd00
	s_ashr_i32 s38, s6, 6
	s_bfe_u32 s37, s16, 0x20004
	s_ashr_i32 s39, s38, 31
	s_lshl_b64 s[6:7], s[38:39], 6
	s_lshl_b32 s8, s37, 4
	s_bfe_u32 s22, s72, 0x40003
	s_or_b32 s8, s6, s8
	s_or_b32 s6, s8, s22
	v_mov_b32_e32 v1, v202
	s_lshl_b64 s[40:41], s[6:7], 16
	s_add_u32 s40, s9, s40
	v_ashrrev_i32_e32 v0, 6, v1
	v_and_b32_e32 v36, 63, v1
	v_ashrrev_i32_e32 v1, 31, v0
	s_addc_u32 s41, s33, s41
	s_lshl_b32 s6, s22, 7
	v_lshlrev_b64 v[4:5], 13, v[0:1]
	v_lshl_add_u32 v0, v0, 4, s6
	s_lshl_b64 s[38:39], s[38:39], 11
	v_ashrrev_i32_e32 v1, 31, v0
	v_lshl_add_u64 v[4:5], s[40:41], 0, v[4:5]
	v_lshlrev_b32_e32 v6, 6, v36
	v_mov_b32_e32 v7, v2
	v_lshl_add_u64 v[38:39], s[38:39], 0, v[0:1]
	v_mov_b64_e32 v[0:1], s[34:35]
	s_movk_i32 s6, 0x1600
	v_lshl_add_u64 v[8:9], v[4:5], 0, v[6:7]
	s_mov_b64 s[40:41], 0x1000
	v_lshl_or_b32 v3, s37, 6, v36
	v_mad_u64_u32 v[40:41], s[38:39], v38, s6, v[0:1]
	v_lshl_add_u64 v[24:25], v[8:9], 0, s[40:41]
	global_load_dwordx4 v[4:7], v[8:9], off offset:48
	global_load_dwordx4 v[12:15], v[8:9], off offset:32
	global_load_dwordx4 v[20:23], v[8:9], off offset:16
	global_load_dwordx4 v[28:31], v[8:9], off
	v_add_co_u32_e32 v8, vcc, s80, v8
	v_mad_i32_i24 v41, v39, s6, v41
	v_lshlrev_b32_e32 v0, 1, v3
	v_mov_b32_e32 v1, v2
	v_addc_co_u32_e32 v9, vcc, 0, v9, vcc
	v_lshl_add_u64 v[40:41], v[40:41], 0, v[0:1]
	v_add_co_u32_e32 v42, vcc, s80, v40
	global_load_dwordx4 v[32:35], v[8:9], off
	s_nop 0
	global_load_dwordx4 v[8:11], v[24:25], off offset:48
	global_load_dwordx4 v[16:19], v[24:25], off offset:32
	s_nop 0
	global_load_dwordx4 v[24:27], v[24:25], off offset:16
	v_addc_co_u32_e32 v43, vcc, 0, v41, vcc
	global_load_ushort v1, v[42:43], off offset:1024
	v_add_co_u32_e32 v42, vcc, s81, v40
	s_movk_i32 s6, 0x4000
	s_nop 0
	v_addc_co_u32_e32 v43, vcc, 0, v41, vcc
	global_load_ushort v55, v[42:43], off offset:2560
	v_add_co_u32_e32 v42, vcc, s6, v40
	s_movk_i32 s6, 0x5000
	s_nop 0
	v_addc_co_u32_e32 v43, vcc, 0, v41, vcc
	global_load_ushort v54, v[42:43], off
	v_add_co_u32_e32 v42, vcc, s6, v40
	s_movk_i32 s6, 0x6000
	s_nop 0
	v_addc_co_u32_e32 v43, vcc, 0, v41, vcc
	global_load_ushort v53, v[42:43], off offset:1536
	v_add_co_u32_e32 v42, vcc, s6, v40
	s_mov_b32 s6, 0x8000
	s_nop 0
	v_addc_co_u32_e32 v43, vcc, 0, v41, vcc
	global_load_ushort v52, v[42:43], off offset:3072
	v_add_co_u32_e32 v42, vcc, s6, v40
	s_mov_b32 s6, 0x9000
	s_nop 0
	v_addc_co_u32_e32 v43, vcc, 0, v41, vcc
	global_load_ushort v51, v[42:43], off offset:512
	v_add_co_u32_e32 v42, vcc, s6, v40
	s_mov_b32 s6, 0xa000
	s_nop 0
	v_addc_co_u32_e32 v43, vcc, 0, v41, vcc
	global_load_ushort v50, v[42:43], off offset:2048
	v_add_co_u32_e32 v42, vcc, s6, v40
	s_mov_b32 s6, 0xc000
	s_nop 0
	v_addc_co_u32_e32 v43, vcc, 0, v41, vcc
	global_load_ushort v49, v[42:43], off offset:3584
	v_add_co_u32_e32 v42, vcc, s6, v40
	s_mov_b32 s6, 0xd000
	s_nop 0
	v_addc_co_u32_e32 v43, vcc, 0, v41, vcc
	global_load_ushort v48, v[42:43], off offset:1024
	v_add_co_u32_e32 v42, vcc, s6, v40
	s_mov_b32 s6, 0xf000
	s_nop 0
	v_addc_co_u32_e32 v43, vcc, 0, v41, vcc
	global_load_ushort v47, v[42:43], off offset:2560
	v_add_co_u32_e32 v42, vcc, s6, v40
	s_mov_b32 s6, 0x10000
	s_nop 0
	v_addc_co_u32_e32 v43, vcc, 0, v41, vcc
	global_load_ushort v46, v[42:43], off
	v_add_co_u32_e32 v42, vcc, s6, v40
	s_cmp_eq_u32 s22, 0
	s_nop 0
	v_addc_co_u32_e32 v43, vcc, 0, v41, vcc
	global_load_ushort v45, v[42:43], off offset:1536
	v_add_co_u32_e32 v42, vcc, 0x11000, v40
	s_nop 1
	v_addc_co_u32_e32 v43, vcc, 0, v41, vcc
	global_load_ushort v44, v[42:43], off offset:3072
	v_add_co_u32_e32 v42, vcc, 0x13000, v40
	s_nop 1
	v_addc_co_u32_e32 v43, vcc, 0, v41, vcc
	v_add_co_u32_e32 v56, vcc, 0x14000, v40
	global_load_ushort v43, v[42:43], off offset:512
	s_nop 0
	v_addc_co_u32_e32 v57, vcc, 0, v41, vcc
	v_add_co_u32_e32 v40, vcc, 0x15000, v40
	global_load_ushort v42, v[56:57], off offset:2048
	s_nop 0
	v_addc_co_u32_e32 v41, vcc, 0, v41, vcc
	global_load_ushort v3, v[40:41], off offset:3584
	s_cbranch_scc1 .LBB0_314
; __device__ __forceinline__ void lru_fix_item(const Params& p, int l, int item) {
;     ...
;     const float* car = p.lru_carry + (((size_t)b * 4 + h) * 16) * 128;
;     float Hin = 0.f;
; #pragma unroll 4
;     for (int s = 0; s < seg; ++s) { const float as = car[s * 128 + lane * 2], hs = car[s * 128 + lane * 2 + 1]; Hin = as * Hin + hs; }
	s_mov_b32 s9, s7
	s_lshl_b64 s[6:7], s[8:9], 9
	s_add_u32 s6, s15, s6
	s_addc_u32 s7, s17, s7
	v_lshlrev_b32_e32 v56, 3, v36
	s_mov_b32 s38, 0x16000
	s_add_u32 s8, s6, 0x1000
	s_addc_u32 s9, s7, 0
	s_cmp_le_u32 s22, 0
	s_cbranch_scc1 .Llrufix_issued
	global_load_dwordx2 v[62:63], v56, s[6:7] offset:0
	s_cmp_le_u32 s22, 1
	s_cbranch_scc1 .Llrufix_issued
	global_load_dwordx2 v[64:65], v56, s[6:7] offset:512
	s_cmp_le_u32 s22, 2
	s_cbranch_scc1 .Llrufix_issued
	global_load_dwordx2 v[66:67], v56, s[6:7] offset:1024
	s_cmp_le_u32 s22, 3
	s_cbranch_scc1 .Llrufix_issued
	global_load_dwordx2 v[68:69], v56, s[6:7] offset:1536
	s_cmp_le_u32 s22, 4
	s_cbranch_scc1 .Llrufix_issued
	global_load_dwordx2 v[70:71], v56, s[6:7] offset:2048
	s_cmp_le_u32 s22, 5
	s_cbranch_scc1 .Llrufix_issued
	global_load_dwordx2 v[72:73], v56, s[6:7] offset:2560
	s_cmp_le_u32 s22, 6
	s_cbranch_scc1 .Llrufix_issued
	global_load_dwordx2 v[74:75], v56, s[6:7] offset:3072
	s_cmp_le_u32 s22, 7
	s_cbranch_scc1 .Llrufix_issued
	global_load_dwordx2 v[76:77], v56, s[6:7] offset:3584
	s_cmp_le_u32 s22, 8
	s_cbranch_scc1 .Llrufix_issued
	global_load_dwordx2 v[78:79], v56, s[8:9] offset:0
	s_cmp_le_u32 s22, 9
	s_cbranch_scc1 .Llrufix_issued
	global_load_dwordx2 v[80:81], v56, s[8:9] offset:512
	s_cmp_le_u32 s22, 10
	s_cbranch_scc1 .Llrufix_issued
	global_load_dwordx2 v[82:83], v56, s[8:9] offset:1024
	s_cmp_le_u32 s22, 11
	s_cbranch_scc1 .Llrufix_issued
	global_load_dwordx2 v[84:85], v56, s[8:9] offset:1536
	s_cmp_le_u32 s22, 12
	s_cbranch_scc1 .Llrufix_issued
	global_load_dwordx2 v[86:87], v56, s[8:9] offset:2048
	s_cmp_le_u32 s22, 13
	s_cbranch_scc1 .Llrufix_issued
	global_load_dwordx2 v[88:89], v56, s[8:9] offset:2560
	s_cmp_le_u32 s22, 14
	s_cbranch_scc1 .Llrufix_issued
	global_load_dwordx2 v[90:91], v56, s[8:9] offset:3072

; #define LAS __attribute__((address_space(3)))
; __device__ __forceinline__ void lds_barrier() { asm volatile("s_waitcnt lgkmcnt(0)" ::: "memory"); __builtin_amdgcn_s_barrier(); asm volatile("" ::: "memory"); }
; __device__ __forceinline__ int opaque_bid() { int t = blockIdx.x; asm volatile("" : "+s"(t)); return t; }
; __device__ __forceinline__ int opaque_gd() { int t = gridDim.x; asm volatile("" : "+s"(t)); return t; }
; __device__ __forceinline__ int opaque_tid() { int t = threadIdx.x; asm volatile("" : "+v"(t)); return t; }
; __device__ __forceinline__ Params fetchP(const LAS Params* lp0) { unsigned la = (unsigned)(unsigned long long)lp0; asm volatile("" : "+v"(la)); const LAS Params* lp = (const LAS Params*)la; Params q; PFIELDS(PFETCH) q.ph_lo = 0; q.ph_hi = 0; return q; }
; __device__ __forceinline__ void lru_item(const Params& p, int l, int item, LAS unsigned char* lds) {
;     const int tid = opaque_tid(), wid = tid >> 6, lane = tid & 63, fr = lane & 15, fq = lane >> 4;
;     const int b = item >> 6, h = (item >> 4) & 3, seg = item & 15;
;     LAS unsigned char* wb = lds + wid * 10752;
;     LAS bf16_t* xa = (LAS bf16_t*)wb; LAS float* xf = (LAS float*)(wb + 2304); LAS float* sa = (LAS float*)(wb + 6528);
;     LAS float* ct = (LAS float*)(lds + 86016);
;     const int t0 = seg * 128 + wid * 16; const size_t Tb = (size_t)b * SEQ;
;     const int ch = h * 64 + lane;
;     lds_barrier();
;     unsigned xr[19];
; #pragma unroll
;     for (int i = 0; i < 19; ++i) { const int t = t0 - 3 + i; xr[i] = (t >= 0) ? (unsigned)p.z[(Tb + (t >= 0 ? t : 0)) * ZLD + 2304 + ch] : 0u; }
; __device__ __forceinline__ void run_phase(const LAS Params* lp, int ph, LAS unsigned char* lds) {
;     ...
;     case 1: for (int it = opaque_bid(); it < 1280; it += opaque_gd()) { const Params p = fetchP(lp); const int jx = (it & ~255) + (it & 7) * 32 + ((it & 255) >> 3);
;             if (it < 256) hgrn_item(p, l, jx, 0, lds); else if (it < 768) attn_item(p, l, jx - 256, lds); else lru_item(p, l, jx - 768, lds); } break;
.LBB0_353:
	v_mov_b32_e32 v0, s84
	ds_read2_b64 v[12:15], v0 offset0:6 offset1:15
	ds_read2_b64 v[16:19], v0 offset0:12 offset1:13
	ds_read2_b64 v[20:23], v0 offset0:17 offset1:31
	ds_read2_b64 v[24:27], v0 offset0:34 offset1:35
	ds_read2_b64 v[8:11], v0 offset0:29 offset1:30
	ds_read2_b64 v[28:31], v0 offset0:37 offset1:38
	ds_read2_b64 v[4:7], v0 offset0:39 offset1:40
	ds_read_b64 v[0:1], v0 offset:328
	s_lshl_b32 s0, s2, 5
	s_and_b32 s39, s2, 0xffffff00
	s_and_b32 s95, s0, 0xe0
	s_or_b32 s69, s95, s39
	s_mov_b64 s[4:5], -1
	s_cmpk_gt_i32 s2, 0xff
	s_waitcnt lgkmcnt(0)
	v_readfirstlane_b32 s26, v12
	v_readfirstlane_b32 s27, v13
	v_readfirstlane_b32 s30, v14
	v_readfirstlane_b32 s31, v15
	v_readfirstlane_b32 s6, v20
	v_readfirstlane_b32 s7, v21
	v_readfirstlane_b32 s10, v22
	v_readfirstlane_b32 s11, v23
	v_readfirstlane_b32 s33, v16
	v_readfirstlane_b32 s44, v17
	v_readfirstlane_b32 s17, v18
	v_readfirstlane_b32 s22, v19
	v_readfirstlane_b32 s70, v24
	v_readfirstlane_b32 s71, v25
	v_readfirstlane_b32 s36, v26
	v_readfirstlane_b32 s37, v27
	v_readfirstlane_b32 s8, v8
	v_readfirstlane_b32 s9, v9
	v_readfirstlane_b32 s15, v10
	v_readfirstlane_b32 s94, v11
	v_readfirstlane_b32 s23, v28
	v_readfirstlane_b32 s97, v29
	v_readfirstlane_b32 s34, v30
	v_readfirstlane_b32 s35, v31
	v_readfirstlane_b32 s41, v4
	v_readfirstlane_b32 s14, v5
	v_readfirstlane_b32 s20, v6
	v_readfirstlane_b32 s21, v7
	v_readfirstlane_b32 s18, v0
	v_readfirstlane_b32 s19, v1
	s_cbranch_scc0 .LBB0_415
	s_bfe_u32 s96, s2, 0x50003
	s_or_b32 s42, s69, s96
	s_cmpk_gt_u32 s2, 0x2ff
	s_cbranch_scc0 .LBB0_400
	s_add_i32 s4, s69, 0xfffffd00
	v_mov_b32_e32 v1, v202
	s_bfe_u32 s38, s42, 0x20004
	s_bfe_u32 s79, s2, 0x40003
	s_ashr_i32 s28, s4, 6
	v_ashrrev_i32_e32 v0, 6, v1
	v_and_b32_e32 v3, 63, v1
	s_lshl_b32 s4, s79, 7
	s_lshl_b32 s16, s38, 6
	s_waitcnt lgkmcnt(0)
	s_barrier
	v_lshl_add_u32 v76, v0, 4, s4
	s_ashr_i32 s29, s28, 31
	v_or_b32_e32 v78, s16, v3
	s_lshl_b64 s[72:73], s[28:29], 11
	v_lshlrev_b32_e32 v4, 1, v78
	v_add_u32_e32 v5, s72, v76
	s_movk_i32 s45, 0x1600
	v_mad_u32_u24 v5, v5, s45, v4
	v_add_u32_e32 v5, 0x1200, v5
	v_add_u32_e32 v102, 0xffffbe00, v5
	v_add_u32_e32 v103, 0xffffd400, v5
	v_add_u32_e32 v104, 0xffffea00, v5
	v_mov_b32_e32 v105, v5
	v_add_u32_e32 v106, 0x1600, v5
	v_add_u32_e32 v107, 0x2c00, v5
	v_add_u32_e32 v108, 0x4200, v5
	v_add_u32_e32 v109, 0x5800, v5
	v_add_u32_e32 v110, 0x6e00, v5
	v_add_u32_e32 v111, 0x8400, v5
	v_add_u32_e32 v112, 0x9a00, v5
	v_add_u32_e32 v113, 0xb000, v5
	v_add_u32_e32 v114, 0xc600, v5
	v_add_u32_e32 v115, 0xdc00, v5
	v_add_u32_e32 v116, 0xf200, v5
	v_add_u32_e32 v117, 0x10800, v5
	v_add_u32_e32 v118, 0x11e00, v5
	v_add_u32_e32 v119, 0x13400, v5
	v_add_u32_e32 v120, 0x14a00, v5
	v_cmp_lt_i32_e32 vcc, 2, v76
	s_nop 1
	v_cndmask_b32_e32 v102, v5, v102, vcc
	v_cmp_lt_i32_e32 vcc, 1, v76
	s_nop 1
	v_cndmask_b32_e32 v103, v5, v103, vcc
	v_cmp_lt_i32_e32 vcc, 0, v76
	s_nop 1
	v_cndmask_b32_e32 v104, v5, v104, vcc
	global_load_ushort v88, v102, s[8:9]
	global_load_ushort v87, v103, s[8:9]
	global_load_ushort v85, v104, s[8:9]
	global_load_ushort v83, v105, s[8:9]
	global_load_ushort v26, v106, s[8:9]
	global_load_ushort v22, v107, s[8:9]
	global_load_ushort v24, v108, s[8:9]
	global_load_ushort v23, v109, s[8:9]
	global_load_ushort v27, v110, s[8:9]
	global_load_ushort v25, v111, s[8:9]
	global_load_ushort v82, v112, s[8:9]
	global_load_ushort v81, v113, s[8:9]
	global_load_ushort v86, v114, s[8:9]
	global_load_ushort v84, v115, s[8:9]
	global_load_ushort v90, v116, s[8:9]
	global_load_ushort v89, v117, s[8:9]
	global_load_ushort v94, v118, s[8:9]
	global_load_ushort v93, v119, s[8:9]
	global_load_ushort v95, v120, s[8:9]
	v_mov_b32_e32 v77, 0
	s_mov_b64 s[74:75], exec

;     __device__ bool next(int i, Unit& u) const {
;         const long L = (long)i * G + c; if (L >= nwg) return false;
;         int wgid = (int)L; { const int q = nwg / NXCD, r = nwg % NXCD, xcd = wgid % NXCD, off = wgid / NXCD; wgid = (xcd < r ? xcd * (q + 1) : r * (q + 1) + (xcd - r) * q) + off; }
;         const int nig = WGM * nN, gid = wgid / nig, fm = gid * WGM, gsz = (nM - fm) < WGM ? (nM - fm) : WGM;
;         u.pm = fm + ((wgid % nig) % gsz); u.pn = (wgid % nig) / gsz; return true;
.LBB0_598:
	s_add_i32 s34, s34, 1
	s_mul_i32 s4, s34, s31
	s_mul_hi_u32 s5, s34, s3
	s_add_i32 s5, s5, s4
	s_mul_i32 s4, s34, s3
	s_add_u32 s12, s4, s1
	s_addc_u32 s13, s5, s96
	v_cmp_gt_i64_e64 s[4:5], s[12:13], v[208:209]
	s_and_b64 vcc, exec, s[4:5]
	s_cbranch_vccnz .LBB0_600
	s_ashr_i32 s8, s12, 31
	s_lshr_b32 s8, s8, 29
	s_add_i32 s8, s12, s8
	s_ashr_i32 s9, s8, 3
	s_and_b32 s8, s8, -8
	s_sub_i32 s8, s12, s8
	s_cmp_lt_i32 s8, 0
	s_movk_i32 s10, 0xd9
	s_cselect_b32 s10, s10, 0xd8
	s_mul_i32 s8, s10, s8
	s_add_i32 s8, s8, s9
	s_mul_hi_i32 s9, s8, 0x1948b0fd
	s_lshr_b32 s10, s9, 31
	s_ashr_i32 s9, s9, 4
	s_add_i32 s9, s9, s10
	s_mul_i32 s10, s9, 6
	s_sub_i32 s11, 64, s10
	s_min_i32 s11, s11, 6
	s_mulk_i32 s9, 0xa2
	s_sub_i32 s9, s8, s9
	s_movk_i32 s26, 0x2aab
	s_cmp_eq_u32 s11, 6
	s_cselect_b32 s26, s26, 0x4000
	s_mul_i32 s8, s9, s26
	s_lshr_b32 s8, s8, 16
	s_mul_i32 s11, s8, s11
	s_sub_i32 s9, s9, s11
	s_add_i32 s10, s9, s10
